# LRU inter-pass handshake reduced to one barrier (sc1 re-reads of own fwd words); P4 row-sum exchange without L1 invalidate
# speedup vs baseline: 1.0083x; 1.0015x over previous
; #define LAS __attribute__((address_space(3)))
; __device__ __forceinline__ int opaque_tid() { int t = threadIdx.x; asm volatile("" : "+v"(t)); return t; }
; #define LDS_BARRIER() do { asm volatile("s_waitcnt lgkmcnt(0)" ::: "memory"); __builtin_amdgcn_s_barrier(); asm volatile("" ::: "memory"); } while (0)
; template <int dir>
; __device__ __forceinline__ void lru_pass(LAS unsigned char* lds, const Params& P, int b, int h, int q, bool dry) {
;     ...
;     {
; #pragma unroll
;         for (int i = 0; i < 2; ++i) { const int idx = tid + i * NTHREADS, gate = idx >> 9, n = (idx >> 4) & 31, kc = idx & 15;
;             *(LAS u32x4*)(WB + (gate * 32 + n) * XC_PITCH + kc * 16) = *(const u32x4*)(LruW + ((size_t)((dir * 2 + gate) * 8 + h) * 128 + q * 32 + n) * 128 + kc * 8); }
;         const float br = -LOG2E * P.lru_ba[(dir * 8 + h) * 128 + chl], bi = -LOG2E * P.lru_bx[(dir * 8 + h) * 128 + chl];
;         const float lam = P.lru_lambda[dir * 1024 + ch];
;         const float cl = -8.0f * LOG2E * log1pf(__expf(-lam));
;     ...
;         if (dir == 0) {
; #pragma unroll
;             for (int i = 0; i < 4; ++i) { const int id = tid + i * NTHREADS; *(u32x4*)(Hg + (size_t)(t0_prev + (id >> 3)) * DM + (id & 7) * 4) = *(const LAS u32x4*)(TOUT + (id >> 3) * IO_WP + (id & 7) * 16); }
;         } else if (!dry) {
; #pragma unroll
;             for (int i = 0; i < 2; ++i) { const int id = tid + i * NTHREADS; *(u32x4*)(Z + ZSLAB(8 + h, (size_t)b * SEQ + t0_prev + (id >> 2)) + q * 32 + (id & 3) * 8) = *(const LAS u32x4*)(TOUT + (id >> 2) * IO_NP + (id & 3) * 16); }
;         }
;     }
; }
; __device__ __forceinline__ void lru_strip(LAS unsigned char* lds, const Params& P, int strip, bool dry) {
;     const int tid = opaque_tid();
;     const int b = strip >> 5, h = (strip >> 2) & 7, q = strip & 3;
;     LAS float* CWL = (LAS float*)(lds + 256 * XC_PITCH + 2048 + 64 * XC_PITCH);
;     for (int i = tid; i < 640; i += NTHREADS) { const int k = i >> 7, c = i & 127; CWL[i] = k < 4 ? P.conv_w[k * 1024 + h * 128 + c] : P.conv_b[h * 128 + c]; }
;     LDS_BARRIER();
;     lru_pass<0>(lds, P, b, h, q, dry);
;     asm volatile("s_waitcnt vmcnt(0)" ::: "memory"); __syncthreads();
;     if (tid < 64) { __builtin_amdgcn_fence(__ATOMIC_ACQUIRE, "agent"); asm volatile("s_waitcnt vmcnt(0)" ::: "memory"); }
;     __syncthreads();
;     lru_pass<1>(lds, P, b, h, q, dry);
.LBB0_303:
	s_waitcnt lgkmcnt(0)
	s_barrier
	v_add_u32_e32 v0, v129, v149
	ds_read_b128 v[0:3], v0
	v_add_u32_e32 v4, s97, v148
	v_ashrrev_i32_e32 v5, 31, v4
	v_lshlrev_b64 v[4:5], 12, v[4:5]
	v_lshl_add_u64 v[8:9], v[130:131], 0, v[4:5]
	v_add_u32_e32 v4, v129, v146
	ds_read_b128 v[4:7], v4
	s_waitcnt lgkmcnt(1)
	global_store_dwordx4 v[8:9], v[0:3], off
	v_cmp_gt_i32_e32 vcc, 64, v128
	s_nop 0
	v_add_u32_e32 v0, s97, v145
	v_ashrrev_i32_e32 v1, 31, v0
	v_lshlrev_b64 v[0:1], 12, v[0:1]
	v_lshl_add_u64 v[0:1], v[130:131], 0, v[0:1]
	s_waitcnt lgkmcnt(0)
	global_store_dwordx4 v[0:1], v[4:7], off
	v_add_u32_e32 v0, v129, v144
	ds_read_b128 v[0:3], v0
	v_add_u32_e32 v4, s97, v143
	v_ashrrev_i32_e32 v5, 31, v4
	v_lshlrev_b64 v[4:5], 12, v[4:5]
	v_lshl_add_u64 v[8:9], v[130:131], 0, v[4:5]
	v_add_u32_e32 v4, v129, v142
	ds_read_b128 v[4:7], v4
	s_waitcnt lgkmcnt(1)
	global_store_dwordx4 v[8:9], v[0:3], off
	s_nop 1
	v_add_u32_e32 v0, s97, v141
	v_ashrrev_i32_e32 v1, 31, v0
	v_lshlrev_b64 v[0:1], 12, v[0:1]
	v_lshl_add_u64 v[0:1], v[130:131], 0, v[0:1]
	s_waitcnt lgkmcnt(0)
	global_store_dwordx4 v[0:1], v[4:7], off
	s_waitcnt lgkmcnt(0)
	v_mov_b32_e32 v32, v167
	s_barrier
	s_or_b32 s0, s26, 16
	v_and_b32_e32 v15, 31, v32
	v_or_b32_e32 v17, s28, v15
	v_add_u32_e32 v13, 0x200, v32
	v_or_b32_e32 v8, s27, v17
	v_ashrrev_i32_e32 v11, 9, v32
	v_ashrrev_i32_e32 v14, 9, v13
	v_lshlrev_b32_e32 v8, 2, v8
	v_mov_b32_e32 v9, v65
	v_lshl_add_u32 v2, v11, 3, s0
	v_lshl_add_u32 v6, v14, 3, s0
	v_lshl_add_u64 v[8:9], s[64:65], 0, v[8:9]
	s_movk_i32 s0, 0x1000
	v_add_co_u32_e32 v8, vcc, s0, v8
	v_and_b32_e32 v12, 15, v32
	s_nop 0
	v_addc_co_u32_e32 v9, vcc, 0, v9, vcc
	global_load_dword v16, v[8:9], off
	v_bfe_u32 v10, v32, 4, 5
	v_lshlrev_b32_e32 v64, 4, v12
	v_ashrrev_i32_e32 v3, 31, v2
	v_ashrrev_i32_e32 v7, 31, v6
	v_or_b32_e32 v4, s28, v10
	v_lshl_add_u64 v[0:1], s[38:39], 0, v[64:65]
	v_lshlrev_b64 v[2:3], 15, v[2:3]
	v_lshlrev_b64 v[6:7], 15, v[6:7]
	v_lshlrev_b32_e32 v4, 8, v4
	v_mov_b32_e32 v5, v65
	v_lshl_add_u64 v[2:3], v[0:1], 0, v[2:3]
	v_lshl_add_u64 v[0:1], v[0:1], 0, v[6:7]
	v_lshl_add_u64 v[2:3], v[2:3], 0, v[4:5]
	v_lshl_add_u64 v[4:5], v[0:1], 0, v[4:5]
	global_load_dwordx4 v[0:3], v[2:3], off
	s_nop 0
	global_load_dwordx4 v[4:7], v[4:5], off
	v_lshrrev_b32_e32 v8, 1, v32
	v_lshlrev_b32_e32 v9, 2, v32
	v_and_b32_e32 v20, 12, v8
	v_lshl_or_b32 v11, v11, 5, v10
	v_add_u32_e32 v8, s88, v64
	v_lshl_or_b32 v14, v14, 5, v10
	v_mad_u64_u32 v[10:11], s[6:7], v11, s89, v[8:9]
	s_or_b32 s8, s26, 8
	v_and_or_b32 v20, v9, 16, v20
	v_lshlrev_b32_e32 v21, 2, v17
	v_mad_u64_u32 v[8:9], s[6:7], v14, s89, v[8:9]
	v_lshl_or_b32 v9, s8, 9, v21
	global_load_dword v14, v9, s[58:59]
	s_nop 0
	global_load_dword v9, v9, s[62:63]
	s_mov_b32 s80, 0x3f2aaaab
	s_mov_b32 s81, 0x3f317218
	s_mov_b32 s91, 0x7f800000
	s_mov_b32 s92, 0x33800000
	v_ashrrev_i32_e32 v33, 4, v32
	v_lshlrev_b32_e32 v34, 3, v12
	v_readfirstlane_b32 s4, v32
	s_lshl_b64 s[0:1], s[78:79], 11
	s_lshl_b32 s5, s8, 14
	s_ashr_i32 s6, s4, 6
	s_add_u32 s26, s0, s5
	s_addc_u32 s27, s1, 0
	s_lshl_b32 s0, s28, 1
	v_readlane_b32 s1, v255, 10
	v_and_b32_e32 v19, 3, v32
	s_add_u32 s0, s1, s0
	v_bfe_u32 v18, v32, 5, 1
	v_add_u32_e32 v44, 0, v64
	v_lshlrev_b32_e32 v64, 4, v19
	s_addc_u32 s1, s3, 0
	v_lshl_add_u64 v[136:137], s[0:1], 0, v[64:65]
	s_lshl_b32 s0, s6, 5
	v_lshlrev_b32_e32 v46, 4, v18
	v_or_b32_e32 v37, s0, v46
	v_add_u32_e32 v158, s86, v64
	v_or_b32_e32 v64, 4, v37
	s_movk_i32 s93, 0x880
	v_ashrrev_i32_e32 v36, 3, v32
	v_ashrrev_i32_e32 v38, 3, v13
	v_ashrrev_i32_e32 v140, 2, v32
	v_sub_u32_e32 v39, 0xff, v37
	v_sub_u32_e32 v64, 0xff, v64
	v_lshl_add_u32 v160, v33, 3, -1
	v_mul_lo_u32 v52, v33, s93
	s_waitcnt vmcnt(3)
	ds_write_b128 v10, v[0:3]
	s_waitcnt vmcnt(2)
	ds_write_b128 v8, v[4:7]
	v_mul_f32_e32 v11, 0xbfb8aa3b, v16
	v_exp_f32_e32 v11, v11
	v_mul_lo_u32 v57, v39, s89
	v_mul_lo_u32 v58, v39, s30
	v_mul_lo_u32 v114, v64, s89
	v_add_f32_e32 v2, 1.0, v11
	v_add_f32_e32 v3, -1.0, v2
	v_frexp_mant_f32_e32 v4, v2
	v_cvt_f64_f32_e32 v[0:1], v2
	v_sub_f32_e32 v5, v3, v2
	v_frexp_exp_i32_f64_e32 v0, v[0:1]
	v_cmp_gt_f32_e32 vcc, s80, v4
	v_sub_f32_e32 v3, v11, v3
	v_add_f32_e32 v1, 1.0, v5
	v_subbrev_co_u32_e32 v0, vcc, 0, v0, vcc
	v_add_f32_e32 v1, v3, v1
	v_sub_u32_e32 v3, 0, v0
	v_ldexp_f32 v2, v2, v3
	v_ldexp_f32 v1, v1, v3
	v_add_f32_e32 v3, -1.0, v2
	v_add_f32_e32 v4, 1.0, v2
	v_add_f32_e32 v5, 1.0, v3
	v_add_f32_e32 v6, -1.0, v4
	v_sub_f32_e32 v5, v2, v5
	v_sub_f32_e32 v2, v2, v6
	v_add_f32_e32 v5, v1, v5
	v_add_f32_e32 v1, v1, v2
	v_add_f32_e32 v7, v4, v1
	v_rcp_f32_e32 v8, v7
	v_add_f32_e32 v2, v3, v5
	v_sub_f32_e32 v4, v7, v4
	v_sub_f32_e32 v3, v2, v3
	v_sub_f32_e32 v1, v1, v4
	v_mul_f32_e32 v4, v2, v8
	v_sub_f32_e32 v3, v5, v3
	v_mul_f32_e32 v5, v7, v4
	v_fma_f32 v10, v4, v7, -v5
	v_fmac_f32_e32 v10, v4, v1
	v_add_f32_e32 v16, v5, v10
	v_sub_f32_e32 v21, v2, v16
	v_sub_f32_e32 v2, v2, v21
	v_sub_f32_e32 v5, v16, v5
	v_sub_f32_e32 v2, v2, v16
	v_sub_f32_e32 v5, v5, v10
	v_add_f32_e32 v2, v3, v2
	v_add_f32_e32 v2, v5, v2
	v_add_f32_e32 v3, v21, v2
	v_mul_f32_e32 v5, v8, v3
	v_sub_f32_e32 v10, v21, v3
	v_mul_f32_e32 v16, v7, v5
	v_add_f32_e32 v2, v2, v10
	v_add_f32_e32 v10, v4, v5
	v_fma_f32 v7, v5, v7, -v16
	v_sub_f32_e32 v4, v10, v4
	v_fmac_f32_e32 v7, v5, v1
	v_sub_f32_e32 v1, v5, v4
	v_add_f32_e32 v4, v16, v7
	v_sub_f32_e32 v5, v4, v16
	v_sub_f32_e32 v16, v3, v4
	v_sub_f32_e32 v3, v3, v16
	v_sub_f32_e32 v3, v3, v4
	v_cvt_f32_i32_e32 v0, v0
	v_sub_f32_e32 v5, v5, v7
	v_add_f32_e32 v2, v2, v3
	v_add_f32_e32 v2, v5, v2
	v_add_f32_e32 v2, v16, v2
	v_mul_f32_e32 v2, v8, v2
	v_mul_f32_e32 v6, 0x3f317218, v0
; #define LAS __attribute__((address_space(3)))
; template <int dir>
; __device__ __forceinline__ void lru_pass(LAS unsigned char* lds, const Params& P, int b, int h, int q, bool dry) {
;     ...
;         const float cl = -8.0f * LOG2E * log1pf(__expf(-lam));
;         float carry = 0.f;
;         LruTile cur = lru_tile(Z, ZC, b, h, dir, 0);
;         u32x4 rows[11];
;         constexpr int NIN = dir == 0 ? 2 : 4;
;         u32x4 inr[NIN];
;         lru_load_rows(rows, cur, tr, cgp);
;     ...
;             const int sbase = 32 * wid + 16 * g;
;             { const int sl = 32 * wid + s_i; const int tlA = dir == 0 ? sl : 255 - sl;
;               const LAS unsigned char* ap = XC + tlA * XC_PITCH + 16 * g;
;               const LAS unsigned char* wrp = WB + nl * XC_PITCH + 16 * g; const LAS unsigned char* wip = wrp + 32 * XC_PITCH;
; #pragma unroll
;               for (int ks = 0; ks < 8; ++ks) { const bf16x8 A = *(const LAS bf16x8*)(ap + 32 * ks);
;                   const bf16x8 Br = *(const LAS bf16x8*)(wrp + 32 * ks), Bi = *(const LAS bf16x8*)(wip + 32 * ks);
;                   zr = __builtin_amdgcn_mfma_f32_32x32x16_bf16(A, Br, zr, 0, 0, 0); zi = __builtin_amdgcn_mfma_f32_32x32x16_bf16(A, Bi, zi, 0, 0, 0); } }
;             unsigned xcb[16], pk[16];
; #pragma unroll
;             for (int v = 0; v < 16; ++v) { const int s = sbase + v; const int tl = dir == 0 ? s : 255 - s; xcb[v] = *(const LAS bf16_t*)(XC + tl * XC_PITCH + chl * 2);
;                 if (dir == 0) pk[v] = *(const LAS bf16_t*)(TIN + tl * IO_NP + nl * 2); else pk[v] = *(const LAS unsigned*)(TIN + tl * IO_WP + nl * 4); }
	v_add_f32_e32 v1, v1, v2
	v_add_f32_e32 v2, v10, v1
	v_fma_f32 v5, v0, s81, -v6
	v_fmac_f32_e32 v5, 0xb102e308, v0
	v_sub_f32_e32 v0, v2, v10
	v_mul_f32_e32 v3, v2, v2
	v_sub_f32_e32 v0, v1, v0
	v_add_f32_e32 v1, v6, v5
	v_fmamk_f32 v4, v3, 0x3e9b6dac, v200
	v_sub_f32_e32 v6, v1, v6
	v_fmaak_f32 v4, v3, v4, 0x3f2aaada
	v_sub_f32_e32 v5, v5, v6
	v_ldexp_f32 v6, v2, 1
	v_mul_f32_e32 v2, v2, v3
	v_mul_f32_e32 v2, v2, v4
	v_add_f32_e32 v3, v6, v2
	v_sub_f32_e32 v4, v3, v6
	v_ldexp_f32 v0, v0, 1
	v_sub_f32_e32 v2, v2, v4
	v_add_f32_e32 v0, v0, v2
	v_add_f32_e32 v2, v3, v0
	v_sub_f32_e32 v3, v2, v3
	v_sub_f32_e32 v0, v0, v3
	v_add_f32_e32 v3, v1, v2
	v_sub_f32_e32 v4, v3, v1
	v_sub_f32_e32 v6, v3, v4
	v_sub_f32_e32 v1, v1, v6
	v_sub_f32_e32 v2, v2, v4
	v_add_f32_e32 v1, v2, v1
	v_add_f32_e32 v2, v5, v0
	v_sub_f32_e32 v4, v2, v5
	v_add_f32_e32 v1, v2, v1
	v_sub_f32_e32 v6, v2, v4
	v_add_f32_e32 v2, v3, v1
	v_sub_f32_e32 v5, v5, v6
	v_sub_f32_e32 v0, v0, v4
	v_sub_f32_e32 v3, v2, v3
	v_add_f32_e32 v0, v0, v5
	v_sub_f32_e32 v1, v1, v3
	v_add_f32_e32 v0, v0, v1
	v_add_f32_e32 v0, v2, v0
	v_cmp_neq_f32_e32 vcc, s91, v11
	v_mov_b32_e32 v1, v65
	v_mul_lo_u32 v115, v64, s30
	v_cndmask_b32_e32 v0, v201, v0, vcc
	v_cmp_ngt_f32_e32 vcc, -1.0, v11
	v_mul_lo_u32 v206, v39, s87
	v_mul_lo_u32 v210, v64, s87
	v_cndmask_b32_e32 v0, v202, v0, vcc
	v_cmp_neq_f32_e32 vcc, -1.0, v11
	v_ashrrev_i32_e32 v39, 31, v38
	v_sub_u32_e32 v41, 0xfe, v37
	v_cndmask_b32_e32 v0, v203, v0, vcc
	v_cmp_lt_f32_e64 vcc, |v11|, s92
	v_mul_lo_u32 v59, v41, s89
	v_mul_lo_u32 v60, v41, s30
	v_cndmask_b32_e32 v6, v0, v11, vcc
	v_lshl_or_b32 v0, v33, 13, v34
	v_lshlrev_b64 v[0:1], 1, v[0:1]
	v_lshl_add_u64 v[2:3], s[48:49], 0, v[0:1]
	v_lshl_add_u64 v[4:5], s[50:51], 0, v[0:1]
	global_load_dwordx4 v[68:71], v[2:3], off offset:-2048
	global_load_dwordx4 v[72:75], v[2:3], off
	global_load_dwordx4 v[76:79], v[2:3], off offset:2048
	global_load_dwordx4 v[80:83], v[4:5], off
	v_lshl_add_u64 v[2:3], s[56:57], 0, v[0:1]
	v_lshl_add_u64 v[4:5], s[60:61], 0, v[0:1]
	global_load_dwordx4 v[84:87], v[2:3], off
	global_load_dwordx4 v[88:91], v[4:5], off
	v_lshl_add_u64 v[2:3], s[66:67], 0, v[0:1]
	v_lshl_add_u64 v[4:5], s[70:71], 0, v[0:1]
	global_load_dwordx4 v[92:95], v[2:3], off
	global_load_dwordx4 v[96:99], v[4:5], off
	v_lshl_add_u64 v[2:3], s[72:73], 0, v[0:1]
	v_lshl_add_u64 v[4:5], s[74:75], 0, v[0:1]
	v_lshl_add_u64 v[0:1], s[76:77], 0, v[0:1]
	global_load_dwordx4 v[100:103], v[2:3], off
	global_load_dwordx4 v[104:107], v[4:5], off
	global_load_dwordx4 v[108:111], v[0:1], off
	v_lshlrev_b32_e32 v2, 4, v32
	v_and_b32_e32 v2, 0x70, v2
	v_lshlrev_b32_e32 v1, 2, v15
	v_add_u32_e32 v45, s95, v2
	v_or3_b32 v2, v19, v20, s0
	s_and_b32 s0, s4, 0x3fffffc0
	v_add_u32_e32 v161, s94, v1
	s_cmp_eq_u32 s6, 7
	v_lshl_add_u32 v254, s0, 2, v161
	s_cselect_b64 s[0:1], -1, 0
	s_cmp_eq_u32 s6, 6
	s_cselect_b64 s[16:17], -1, 0
	s_cmp_eq_u32 s6, 5
	s_cselect_b64 s[4:5], -1, 0
	s_cmp_eq_u32 s6, 4
	s_cselect_b64 s[8:9], -1, 0
	s_cmp_eq_u32 s6, 3
	s_cselect_b64 s[10:11], -1, 0
	s_cmp_eq_u32 s6, 2
	s_cselect_b64 s[12:13], -1, 0
	s_cmp_eq_u32 s6, 1
	s_cselect_b64 s[14:15], -1, 0
	s_lshl_b32 s6, s25, 7
	s_and_b32 s6, s6, 0xe00
	s_lshl_b32 s7, s29, 7
	s_or_b32 s6, s7, s6
	s_add_u32 s6, s6, s44
	v_add_u32_e32 v50, s95, v1
	v_add_u32_e32 v1, 0x400, v32
	s_addc_u32 s7, 0, s45
	v_ashrrev_i32_e32 v40, 3, v1
	v_add_u32_e32 v1, 0x600, v32
	v_and_b32_e32 v32, 7, v32
	s_add_u32 s18, s84, s46
	v_lshlrev_b32_e32 v64, 4, v32
	v_lshl_or_b32 v32, v33, 10, v34
	v_mov_b32_e32 v33, v65
	s_addc_u32 s19, s85, s47
	v_lshl_add_u64 v[144:145], v[32:33], 1, s[18:19]
	v_lshlrev_b64 v[32:33], 12, v[38:39]
	v_lshl_add_u64 v[32:33], s[6:7], 0, v[32:33]
	v_mul_lo_u32 v207, v41, s87
	v_lshl_add_u64 v[32:33], v[32:33], 0, v[64:65]
	v_ashrrev_i32_e32 v41, 31, v40
	v_or_b32_e32 v43, 2, v37
	v_lshl_add_u64 v[252:253], s[42:43], 0, v[32:33]
	v_lshlrev_b64 v[32:33], 12, v[40:41]
	v_ashrrev_i32_e32 v42, 3, v1
	v_sub_u32_e32 v43, 0xff, v43
	v_or_b32_e32 v63, 3, v37
	v_or_b32_e32 v66, 5, v37
	v_or_b32_e32 v67, 6, v37
	v_or_b32_e32 v120, 7, v37
	v_or_b32_e32 v123, 8, v37
	v_or_b32_e32 v126, 9, v37
	v_or_b32_e32 v129, 10, v37
	v_or_b32_e32 v132, 11, v37
	v_or_b32_e32 v135, 12, v37
	v_or_b32_e32 v142, 13, v37
	v_or_b32_e32 v143, 14, v37
	v_or_b32_e32 v37, 15, v37
	v_lshl_add_u64 v[32:33], s[6:7], 0, v[32:33]
	v_mul_lo_u32 v61, v43, s89
	v_mul_lo_u32 v62, v43, s30
	v_sub_u32_e32 v37, 0xff, v37
	v_mul_lo_u32 v208, v43, s87
	v_lshl_add_u64 v[32:33], v[32:33], 0, v[64:65]
	v_ashrrev_i32_e32 v43, 31, v42
	v_sub_u32_e32 v2, 0xff, v2
	v_mul_lo_u32 v204, v37, s89
	v_mul_lo_u32 v205, v37, s30
	v_mul_lo_u32 v221, v37, s87
	v_ashrrev_i32_e32 v37, 31, v36
	v_lshl_add_u64 v[154:155], s[42:43], 0, v[32:33]
	v_lshlrev_b64 v[32:33], 12, v[42:43]
	v_mul_lo_u32 v2, v2, s89
	v_mul_lo_u32 v53, v36, s30
	v_sub_u32_e32 v63, 0xff, v63
	v_sub_u32_e32 v66, 0xff, v66
	v_sub_u32_e32 v67, 0xff, v67
	v_sub_u32_e32 v120, 0xff, v120
	v_sub_u32_e32 v123, 0xff, v123
	v_sub_u32_e32 v126, 0xff, v126
	v_lshlrev_b64 v[36:37], 12, v[36:37]
	v_lshl_add_u64 v[32:33], s[6:7], 0, v[32:33]
	v_lshlrev_b32_e32 v35, 5, v12
	v_add_u32_e32 v47, 0, v2
	v_mov_b32_e32 v2, s88
	v_lshl_add_u32 v49, v17, 1, 0
	v_lshl_add_u32 v51, v15, 1, s86
	v_mul_lo_u32 v112, v63, s89
	v_mul_lo_u32 v113, v63, s30
	v_mul_lo_u32 v116, v66, s89
	v_mul_lo_u32 v117, v66, s30
	v_mul_lo_u32 v118, v67, s89
	v_mul_lo_u32 v119, v67, s30
	v_mul_lo_u32 v121, v120, s89
	v_mul_lo_u32 v122, v120, s30
	v_mul_lo_u32 v124, v123, s89
	v_mul_lo_u32 v125, v123, s30
	v_mul_lo_u32 v127, v126, s89
	v_mul_lo_u32 v128, v126, s30
	v_sub_u32_e32 v129, 0xff, v129
	v_sub_u32_e32 v132, 0xff, v132
	v_sub_u32_e32 v135, 0xff, v135
	v_sub_u32_e32 v142, 0xff, v142
	v_sub_u32_e32 v143, 0xff, v143
	v_mul_lo_u32 v211, v66, s87
	v_mul_lo_u32 v212, v67, s87
	v_mul_lo_u32 v120, v120, s87
	v_mul_lo_u32 v123, v123, s87
	v_mul_lo_u32 v126, v126, s87
	v_lshl_add_u64 v[36:37], s[6:7], 0, v[36:37]
	v_lshl_add_u64 v[32:33], v[32:33], 0, v[64:65]
	v_mov_b32_e32 v66, v65
	v_mov_b32_e32 v67, v65
	s_waitcnt vmcnt(12)
; #define LAS __attribute__((address_space(3)))
; template <int dir>
; __device__ __forceinline__ void lru_pass(LAS unsigned char* lds, const Params& P, int b, int h, int q, bool dry) {
;     ...
;         for (int sc = 0; sc < 9; ++sc) {
;             const bool isctx = (sc == 0);
;             const int t0 = cur.t0;
; #pragma unroll
;             for (int j = 0; j < 11; ++j) { if (j != 0 && j < 9) continue;
;                 const int t = t0 + tr * 8 - 1 + j; if (t < 0 || t >= cur.L) rows[j] = (u32x4){0u, 0u, 0u, 0u}; }
;             f32x2 cw2[4][4], cb2[4];
; #pragma unroll
;             for (int k = 0; k < 5; ++k) { const f32x4 a = *(const LAS f32x4*)(CWL + k * 128 + cgp * 8), c2 = *(const LAS f32x4*)(CWL + k * 128 + cgp * 8 + 4);
;                 if (k < 4) { cw2[k][0] = (f32x2){a[0], a[1]}; cw2[k][1] = (f32x2){a[2], a[3]}; cw2[k][2] = (f32x2){c2[0], c2[1]}; cw2[k][3] = (f32x2){c2[2], c2[3]}; }
;                 else { cb2[0] = (f32x2){a[0], a[1]}; cb2[1] = (f32x2){a[2], a[3]}; cb2[2] = (f32x2){c2[0], c2[1]}; cb2[3] = (f32x2){c2[2], c2[3]}; } }
;     ...
;             for (int v = 0; v < 16; ++v) { zr[v] = br; zi[v] = bi; }
	v_mul_f32_e32 v0, 0xbfb8aa3b, v14
	s_waitcnt vmcnt(11)
	v_mul_f32_e32 v16, 0xbfb8aa3b, v9
	v_mad_u32_u24 v48, v15, s89, v2
	v_mul_lo_u32 v54, v38, s30
	v_mul_lo_u32 v55, v40, s30
	v_mul_lo_u32 v56, v42, s30
	v_ashrrev_i32_e32 v138, 2, v13
	v_mul_lo_u32 v130, v129, s89
	v_mul_lo_u32 v131, v129, s30
	v_mul_lo_u32 v133, v132, s89
	v_mul_lo_u32 v134, v132, s30
	v_mul_lo_u32 v146, v135, s89
	v_mul_lo_u32 v147, v135, s30
	v_mul_lo_u32 v148, v142, s89
	v_mul_lo_u32 v149, v142, s30
	v_mul_lo_u32 v162, v143, s89
	v_mul_lo_u32 v163, v143, s30
	v_mul_lo_u32 v63, v63, s87
	v_mul_lo_u32 v129, v129, s87
	v_mul_lo_u32 v132, v132, s87
	v_mul_lo_u32 v135, v135, s87
	v_mul_lo_u32 v219, v142, s87
	v_mul_lo_u32 v220, v143, s87
	v_lshl_add_u64 v[36:37], v[36:37], 0, v[64:65]
	v_lshl_add_u64 v[150:151], s[42:43], 0, v[32:33]
	v_mov_b32_e32 v64, v65
	v_add_u32_e32 v32, 0, v35
	v_add_u32_e32 v180, v49, v112
	v_add_u32_e32 v181, v50, v113
	v_add_u32_e32 v182, v49, v114
	v_add_u32_e32 v183, v50, v115
	v_add_u32_e32 v184, v49, v116
	v_add_u32_e32 v185, v50, v117
	v_add_u32_e32 v186, v49, v118
	v_add_u32_e32 v187, v50, v119
	v_add_u32_e32 v188, v49, v121
	v_add_u32_e32 v189, v50, v122
	v_add_u32_e32 v190, v49, v124
	v_add_u32_e32 v191, v50, v125
	v_add_u32_e32 v192, v49, v127
	v_add_u32_e32 v213, v51, v120
	v_add_u32_e32 v214, v51, v123
	v_add_u32_e32 v215, v51, v126
	v_mov_b64_e32 v[114:115], v[66:67]
	v_mov_b64_e32 v[118:119], v[66:67]
	v_mov_b64_e32 v[122:123], v[66:67]
	v_mov_b64_e32 v[126:127], v[66:67]
	s_mov_b32 s78, 0
	v_mov_b32_e32 v156, 0xff800000
	v_mul_f32_e32 v159, 0xc138aa3b, v6
	v_cmp_eq_u32_e32 vcc, 0, v18
	v_mul_lo_u32 v164, v140, s87
	v_ashrrev_i32_e32 v141, 31, v140
	v_mul_lo_u32 v152, v138, s87
	v_ashrrev_i32_e32 v139, 31, v138
	v_mov_b32_e32 v1, v0
	v_mov_b32_e32 v2, v0
	v_mov_b32_e32 v3, v0
	v_mov_b32_e32 v4, v0
	v_mov_b32_e32 v5, v0
	v_mov_b32_e32 v6, v0
	v_mov_b32_e32 v7, v0
	v_mov_b32_e32 v8, v0
	v_mov_b32_e32 v9, v0
	v_mov_b32_e32 v10, v0
	v_mov_b32_e32 v11, v0
	v_mov_b32_e32 v12, v0
	v_mov_b32_e32 v13, v0
	v_mov_b32_e32 v14, v0
	v_mov_b32_e32 v15, v0
	v_mov_b32_e32 v17, v16
	v_mov_b32_e32 v18, v16
	v_mov_b32_e32 v19, v16
	v_mov_b32_e32 v20, v16
	v_mov_b32_e32 v21, v16
	v_mov_b32_e32 v22, v16
	v_mov_b32_e32 v23, v16
	v_mov_b32_e32 v24, v16
	v_mov_b32_e32 v25, v16
	v_mov_b32_e32 v26, v16
	v_mov_b32_e32 v27, v16
	v_mov_b32_e32 v28, v16
	v_mov_b32_e32 v29, v16
	v_mov_b32_e32 v30, v16
	v_mov_b32_e32 v31, v16
	v_lshl_add_u64 v[142:143], s[42:43], 0, v[36:37]
	s_movk_i32 s28, 0x100
	v_mov_b32_e32 v222, 0
	s_mov_b64 s[44:45], 0
	s_movk_i32 s25, 0x700
	v_add_u32_e32 v165, 0x15c00, v32
	v_add_u32_e32 v166, v44, v52
	v_add_u32_e32 v168, v45, v53
	v_add_u32_e32 v169, v45, v54
	v_add_u32_e32 v170, v45, v55
	v_add_u32_e32 v171, v45, v56
	v_add_u32_e32 v172, v47, v46
	v_add_u32_e32 v173, v48, v46
	v_add_u32_e32 v174, v49, v57
	v_add_u32_e32 v175, v50, v58
	v_add_u32_e32 v176, v49, v59
	v_add_u32_e32 v177, v50, v60
	v_add_u32_e32 v178, v49, v61
	v_add_u32_e32 v179, v50, v62
	v_add_u32_e32 v193, v50, v128
	v_add_u32_e32 v194, v49, v130
	v_add_u32_e32 v195, v50, v131
	v_add_u32_e32 v196, v49, v133
	v_add_u32_e32 v197, v50, v134
	v_add_u32_e32 v198, v49, v146
	v_add_u32_e32 v199, v50, v147
	v_add_u32_e32 v200, v49, v148
	v_add_u32_e32 v201, v50, v149
	v_add_u32_e32 v202, v49, v162
	v_add_u32_e32 v203, v50, v163
	v_add_u32_e32 v204, v49, v204
	v_add_u32_e32 v205, v50, v205
	v_add_u32_e32 v206, v51, v206
	v_add_u32_e32 v207, v51, v207
	v_add_u32_e32 v208, v51, v208
	v_add_u32_e32 v209, v51, v63
	v_add_u32_e32 v210, v51, v210
	v_add_u32_e32 v211, v51, v211
	v_add_u32_e32 v212, v51, v212
	v_add_u32_e32 v216, v51, v129
	v_add_u32_e32 v217, v51, v132
	v_add_u32_e32 v218, v51, v135
	v_add_u32_e32 v219, v51, v219
	v_add_u32_e32 v220, v51, v220
	v_add_u32_e32 v221, v51, v221
	v_mov_b64_e32 v[112:113], v[64:65]
	v_mov_b64_e32 v[116:117], v[64:65]
	v_mov_b64_e32 v[120:121], v[64:65]
	v_mov_b64_e32 v[124:125], v[64:65]
	s_mov_b32 s46, 0
	s_mov_b32 s29, 0
.LBB0_306:
	v_add_u32_e32 v32, s29, v160
	v_cmp_lt_i32_e64 s[18:19], -1, v32
	v_cmp_gt_i32_e64 s[20:21], s28, v32
	s_and_b64 s[18:19], s[18:19], s[20:21]
	v_add_u32_e32 v33, 9, v32
	s_waitcnt vmcnt(10)
	v_cndmask_b32_e64 v71, 0, v71, s[18:19]
	v_cndmask_b32_e64 v70, 0, v70, s[18:19]
	v_cndmask_b32_e64 v69, 0, v69, s[18:19]
	v_cndmask_b32_e64 v68, 0, v68, s[18:19]
	v_cmp_lt_i32_e64 s[18:19], -10, v32
	v_cmp_gt_i32_e64 s[20:21], s28, v33
	s_and_b64 s[18:19], s[18:19], s[20:21]
	v_add_u32_e32 v33, 10, v32
	s_waitcnt vmcnt(1)
	v_cndmask_b32_e64 v107, 0, v107, s[18:19]
	v_cndmask_b32_e64 v106, 0, v106, s[18:19]
	v_cndmask_b32_e64 v105, 0, v105, s[18:19]
	v_cndmask_b32_e64 v104, 0, v104, s[18:19]
	v_cmp_lt_i32_e64 s[18:19], -11, v32
	v_cmp_gt_i32_e64 s[20:21], s28, v33
	ds_read_b128 v[60:63], v165
	ds_read_b128 v[52:55], v165 offset:16
	ds_read_b128 v[44:47], v165 offset:528
	ds_read_b128 v[56:59], v165 offset:512
	ds_read_b128 v[40:43], v165 offset:1040
	ds_read_b128 v[48:51], v165 offset:1024
	ds_read_b128 v[128:131], v165 offset:2064
	ds_read_b128 v[132:135], v165 offset:2048
	ds_read_b128 v[32:35], v165 offset:1552
	ds_read_b128 v[36:39], v165 offset:1536
	v_lshlrev_b32_e32 v66, 16, v68
	v_and_b32_e32 v67, 0xffff0000, v68
	v_lshlrev_b32_e32 v148, 16, v70
	v_and_b32_e32 v149, 0xffff0000, v70
	s_waitcnt lgkmcnt(2)
; #define LAS __attribute__((address_space(3)))
; __device__ __forceinline__ unsigned cvt_pk_bf16(float lo, float hi) { unsigned r; asm volatile("v_cvt_pk_bf16_f32 %0, %1, %2" : "=v"(r) : "v"(lo), "v"(hi)); return r; }
; __device__ __forceinline__ float bf_lo(unsigned u) { return __uint_as_float(u << 16); }
; __device__ __forceinline__ float bf_hi(unsigned u) { return __uint_as_float(u & 0xffff0000u); }
; template <int dir>
; __device__ __forceinline__ void lru_pass(LAS unsigned char* lds, const Params& P, int b, int h, int q, bool dry) {
;     ...
; #pragma unroll
;             for (int j = 0; j < 8; ++j) {
;                 f32x2 o0 = cb2[0], o1 = cb2[1], o2 = cb2[2], o3 = cb2[3];
; #pragma unroll
;                 for (int k = 0; k < 4; ++k) { const u32x4 rr = rows[j + k];
;                     o0 = cw2[k][0] * (f32x2){bf_lo(rr.x), bf_hi(rr.x)} + o0; o1 = cw2[k][1] * (f32x2){bf_lo(rr.y), bf_hi(rr.y)} + o1;
;                     o2 = cw2[k][2] * (f32x2){bf_lo(rr.z), bf_hi(rr.z)} + o2; o3 = cw2[k][3] * (f32x2){bf_lo(rr.w), bf_hi(rr.w)} + o3; }
;                 u32x4 w; w.x = cvt_pk_bf16(o0[0], o0[1]); w.y = cvt_pk_bf16(o1[0], o1[1]); w.z = cvt_pk_bf16(o2[0], o2[1]); w.w = cvt_pk_bf16(o3[0], o3[1]);
;                 *(LAS u32x4*)(XC + (tr * 8 + j) * XC_PITCH + cgp * 16) = w;
;             }
	v_pk_fma_f32 v[66:67], v[60:61], v[66:67], v[132:133]
	v_lshlrev_b32_e32 v146, 16, v69
	v_and_b32_e32 v147, 0xffff0000, v69
	v_pk_fma_f32 v[148:149], v[52:53], v[148:149], v[128:129]
	v_lshlrev_b32_e32 v224, 16, v71
	v_and_b32_e32 v225, 0xffff0000, v71
	v_lshlrev_b32_e32 v228, 16, v72
	v_and_b32_e32 v229, 0xffff0000, v72
	v_lshlrev_b32_e32 v232, 16, v74
	v_and_b32_e32 v233, 0xffff0000, v74
	v_pk_fma_f32 v[146:147], v[62:63], v[146:147], v[134:135]
	v_pk_fma_f32 v[224:225], v[54:55], v[224:225], v[130:131]
	v_pk_fma_f32 v[66:67], v[56:57], v[228:229], v[66:67]
	v_lshlrev_b32_e32 v230, 16, v73
	v_and_b32_e32 v231, 0xffff0000, v73
	v_pk_fma_f32 v[148:149], v[44:45], v[232:233], v[148:149]
	v_lshlrev_b32_e32 v234, 16, v75
	v_and_b32_e32 v235, 0xffff0000, v75
	v_lshlrev_b32_e32 v236, 16, v76
	v_and_b32_e32 v237, 0xffff0000, v76
	v_lshlrev_b32_e32 v240, 16, v78
	v_and_b32_e32 v241, 0xffff0000, v78
	v_pk_fma_f32 v[146:147], v[58:59], v[230:231], v[146:147]
	v_pk_fma_f32 v[224:225], v[46:47], v[234:235], v[224:225]
	v_pk_fma_f32 v[66:67], v[48:49], v[236:237], v[66:67]
	v_lshlrev_b32_e32 v238, 16, v77
	v_and_b32_e32 v239, 0xffff0000, v77
	v_pk_fma_f32 v[148:149], v[40:41], v[240:241], v[148:149]
	v_lshlrev_b32_e32 v242, 16, v79
	v_and_b32_e32 v243, 0xffff0000, v79
	v_lshlrev_b32_e32 v244, 16, v80
	v_and_b32_e32 v245, 0xffff0000, v80
	v_lshlrev_b32_e32 v248, 16, v82
	v_and_b32_e32 v249, 0xffff0000, v82
	v_pk_fma_f32 v[146:147], v[50:51], v[238:239], v[146:147]
	v_pk_fma_f32 v[224:225], v[42:43], v[242:243], v[224:225]
	s_waitcnt lgkmcnt(0)
	v_pk_fma_f32 v[66:67], v[36:37], v[244:245], v[66:67]
	v_lshlrev_b32_e32 v246, 16, v81
	v_and_b32_e32 v247, 0xffff0000, v81
	v_pk_fma_f32 v[148:149], v[32:33], v[248:249], v[148:149]
	v_lshlrev_b32_e32 v250, 16, v83
	v_and_b32_e32 v251, 0xffff0000, v83
	v_pk_fma_f32 v[146:147], v[38:39], v[246:247], v[146:147]
	v_pk_fma_f32 v[162:163], v[34:35], v[250:251], v[224:225]
	v_cvt_pk_bf16_f32 v224, v66, v67
	v_cvt_pk_bf16_f32 v225, v146, v147
	v_cvt_pk_bf16_f32 v226, v148, v149
	v_pk_fma_f32 v[66:67], v[60:61], v[228:229], v[132:133]
	v_pk_fma_f32 v[148:149], v[52:53], v[232:233], v[128:129]
	v_pk_fma_f32 v[146:147], v[62:63], v[230:231], v[134:135]
	v_pk_fma_f32 v[66:67], v[56:57], v[236:237], v[66:67]
	v_pk_fma_f32 v[148:149], v[44:45], v[240:241], v[148:149]
	v_pk_fma_f32 v[146:147], v[58:59], v[238:239], v[146:147]
	v_pk_fma_f32 v[66:67], v[48:49], v[244:245], v[66:67]
	v_pk_fma_f32 v[148:149], v[40:41], v[248:249], v[148:149]
	v_lshlrev_b32_e32 v228, 16, v84
	v_and_b32_e32 v229, 0xffff0000, v84
	v_lshlrev_b32_e32 v232, 16, v86
	v_and_b32_e32 v233, 0xffff0000, v86
	v_cvt_pk_bf16_f32 v227, v162, v163
	v_pk_fma_f32 v[162:163], v[54:55], v[234:235], v[130:131]
	v_pk_fma_f32 v[146:147], v[50:51], v[246:247], v[146:147]
	v_pk_fma_f32 v[66:67], v[36:37], v[228:229], v[66:67]
	v_lshlrev_b32_e32 v230, 16, v85
	v_and_b32_e32 v231, 0xffff0000, v85
	v_pk_fma_f32 v[148:149], v[32:33], v[232:233], v[148:149]
	ds_write_b128 v166, v[224:227]
	v_pk_fma_f32 v[162:163], v[46:47], v[242:243], v[162:163]
	v_pk_fma_f32 v[146:147], v[38:39], v[230:231], v[146:147]
	v_cvt_pk_bf16_f32 v224, v66, v67
	v_pk_fma_f32 v[66:67], v[60:61], v[236:237], v[132:133]
	v_cvt_pk_bf16_f32 v225, v146, v147
	v_cvt_pk_bf16_f32 v226, v148, v149
	v_pk_fma_f32 v[148:149], v[52:53], v[240:241], v[128:129]
	v_pk_fma_f32 v[162:163], v[42:43], v[250:251], v[162:163]
	v_lshlrev_b32_e32 v234, 16, v87
	v_and_b32_e32 v235, 0xffff0000, v87
	v_pk_fma_f32 v[146:147], v[62:63], v[238:239], v[134:135]
	v_pk_fma_f32 v[66:67], v[56:57], v[244:245], v[66:67]
	v_pk_fma_f32 v[148:149], v[44:45], v[248:249], v[148:149]
	v_pk_fma_f32 v[162:163], v[34:35], v[234:235], v[162:163]
	v_pk_fma_f32 v[146:147], v[58:59], v[246:247], v[146:147]
	v_pk_fma_f32 v[66:67], v[48:49], v[228:229], v[66:67]
	v_pk_fma_f32 v[148:149], v[40:41], v[232:233], v[148:149]
	v_lshlrev_b32_e32 v236, 16, v88
	v_and_b32_e32 v237, 0xffff0000, v88
	v_lshlrev_b32_e32 v240, 16, v90
	v_and_b32_e32 v241, 0xffff0000, v90
	v_cvt_pk_bf16_f32 v227, v162, v163
	v_pk_fma_f32 v[162:163], v[54:55], v[242:243], v[130:131]
	v_pk_fma_f32 v[146:147], v[50:51], v[230:231], v[146:147]
	v_pk_fma_f32 v[66:67], v[36:37], v[236:237], v[66:67]
	v_lshlrev_b32_e32 v238, 16, v89
	v_and_b32_e32 v239, 0xffff0000, v89
	v_pk_fma_f32 v[148:149], v[32:33], v[240:241], v[148:149]
	ds_write_b128 v166, v[224:227] offset:272
	v_pk_fma_f32 v[162:163], v[46:47], v[250:251], v[162:163]
	v_pk_fma_f32 v[146:147], v[38:39], v[238:239], v[146:147]
	v_cvt_pk_bf16_f32 v224, v66, v67
	v_pk_fma_f32 v[66:67], v[60:61], v[244:245], v[132:133]
	v_cvt_pk_bf16_f32 v225, v146, v147
	v_cvt_pk_bf16_f32 v226, v148, v149
	v_pk_fma_f32 v[148:149], v[52:53], v[248:249], v[128:129]
	v_pk_fma_f32 v[162:163], v[42:43], v[234:235], v[162:163]
	v_lshlrev_b32_e32 v242, 16, v91
	v_and_b32_e32 v243, 0xffff0000, v91
	v_pk_fma_f32 v[146:147], v[62:63], v[246:247], v[134:135]
	v_pk_fma_f32 v[66:67], v[56:57], v[228:229], v[66:67]
	v_pk_fma_f32 v[148:149], v[44:45], v[232:233], v[148:149]
	v_pk_fma_f32 v[162:163], v[34:35], v[242:243], v[162:163]
	v_pk_fma_f32 v[146:147], v[58:59], v[230:231], v[146:147]
	v_pk_fma_f32 v[66:67], v[48:49], v[236:237], v[66:67]
	v_pk_fma_f32 v[148:149], v[40:41], v[240:241], v[148:149]
	v_lshlrev_b32_e32 v244, 16, v92
	v_and_b32_e32 v245, 0xffff0000, v92
	v_lshlrev_b32_e32 v248, 16, v94
	v_and_b32_e32 v249, 0xffff0000, v94
	v_cvt_pk_bf16_f32 v227, v162, v163
	v_pk_fma_f32 v[162:163], v[54:55], v[250:251], v[130:131]
	v_pk_fma_f32 v[146:147], v[50:51], v[238:239], v[146:147]
	v_pk_fma_f32 v[66:67], v[36:37], v[244:245], v[66:67]
; #define LAS __attribute__((address_space(3)))
; __device__ __forceinline__ unsigned cvt_pk_bf16(float lo, float hi) { unsigned r; asm volatile("v_cvt_pk_bf16_f32 %0, %1, %2" : "=v"(r) : "v"(lo), "v"(hi)); return r; }
; __device__ __forceinline__ float bf_lo(unsigned u) { return __uint_as_float(u << 16); }
; __device__ __forceinline__ float bf_hi(unsigned u) { return __uint_as_float(u & 0xffff0000u); }
; template <int dir>
; __device__ __forceinline__ void lru_pass(LAS unsigned char* lds, const Params& P, int b, int h, int q, bool dry) {
;     ...
; #pragma unroll
;             for (int j = 0; j < 8; ++j) {
;                 f32x2 o0 = cb2[0], o1 = cb2[1], o2 = cb2[2], o3 = cb2[3];
; #pragma unroll
;                 for (int k = 0; k < 4; ++k) { const u32x4 rr = rows[j + k];
;                     o0 = cw2[k][0] * (f32x2){bf_lo(rr.x), bf_hi(rr.x)} + o0; o1 = cw2[k][1] * (f32x2){bf_lo(rr.y), bf_hi(rr.y)} + o1;
;                     o2 = cw2[k][2] * (f32x2){bf_lo(rr.z), bf_hi(rr.z)} + o2; o3 = cw2[k][3] * (f32x2){bf_lo(rr.w), bf_hi(rr.w)} + o3; }
;                 u32x4 w; w.x = cvt_pk_bf16(o0[0], o0[1]); w.y = cvt_pk_bf16(o1[0], o1[1]); w.z = cvt_pk_bf16(o2[0], o2[1]); w.w = cvt_pk_bf16(o3[0], o3[1]);
;                 *(LAS u32x4*)(XC + (tr * 8 + j) * XC_PITCH + cgp * 16) = w;
;             }
; #pragma unroll
;             for (int i = 0; i < NIN; ++i) { const int id = tid + i * NTHREADS;
;                 if (dir == 0) *(LAS u32x4*)(TIN + (id >> 2) * IO_NP + (id & 3) * 16) = inr[i];
;                 else *(LAS u32x4*)(TIN + (id >> 3) * IO_WP + (id & 7) * 16) = inr[i]; }
	v_lshlrev_b32_e32 v246, 16, v93
	v_and_b32_e32 v247, 0xffff0000, v93
	v_pk_fma_f32 v[148:149], v[32:33], v[248:249], v[148:149]
	ds_write_b128 v166, v[224:227] offset:544
	v_pk_fma_f32 v[162:163], v[46:47], v[234:235], v[162:163]
	v_pk_fma_f32 v[146:147], v[38:39], v[246:247], v[146:147]
	v_cvt_pk_bf16_f32 v224, v66, v67
	v_pk_fma_f32 v[66:67], v[60:61], v[228:229], v[132:133]
	v_cvt_pk_bf16_f32 v225, v146, v147
	v_cvt_pk_bf16_f32 v226, v148, v149
	v_pk_fma_f32 v[148:149], v[52:53], v[232:233], v[128:129]
	v_pk_fma_f32 v[162:163], v[42:43], v[242:243], v[162:163]
	v_lshlrev_b32_e32 v250, 16, v95
	v_and_b32_e32 v251, 0xffff0000, v95
	v_pk_fma_f32 v[146:147], v[62:63], v[230:231], v[134:135]
	v_pk_fma_f32 v[66:67], v[56:57], v[236:237], v[66:67]
	v_pk_fma_f32 v[148:149], v[44:45], v[240:241], v[148:149]
	v_pk_fma_f32 v[162:163], v[34:35], v[250:251], v[162:163]
	v_pk_fma_f32 v[146:147], v[58:59], v[238:239], v[146:147]
	v_pk_fma_f32 v[66:67], v[48:49], v[244:245], v[66:67]
	v_pk_fma_f32 v[148:149], v[40:41], v[248:249], v[148:149]
	v_lshlrev_b32_e32 v228, 16, v96
	v_and_b32_e32 v229, 0xffff0000, v96
	v_lshlrev_b32_e32 v232, 16, v98
	v_and_b32_e32 v233, 0xffff0000, v98
	v_cvt_pk_bf16_f32 v227, v162, v163
	v_pk_fma_f32 v[162:163], v[54:55], v[234:235], v[130:131]
	v_pk_fma_f32 v[146:147], v[50:51], v[246:247], v[146:147]
	v_pk_fma_f32 v[66:67], v[36:37], v[228:229], v[66:67]
	v_lshlrev_b32_e32 v230, 16, v97
	v_and_b32_e32 v231, 0xffff0000, v97
	v_pk_fma_f32 v[148:149], v[32:33], v[232:233], v[148:149]
	ds_write_b128 v166, v[224:227] offset:816
	v_pk_fma_f32 v[162:163], v[46:47], v[242:243], v[162:163]
	v_pk_fma_f32 v[146:147], v[38:39], v[230:231], v[146:147]
	v_cvt_pk_bf16_f32 v224, v66, v67
	v_pk_fma_f32 v[66:67], v[60:61], v[236:237], v[132:133]
	v_cvt_pk_bf16_f32 v225, v146, v147
	v_cvt_pk_bf16_f32 v226, v148, v149
	v_pk_fma_f32 v[148:149], v[52:53], v[240:241], v[128:129]
	v_pk_fma_f32 v[162:163], v[42:43], v[250:251], v[162:163]
	v_lshlrev_b32_e32 v234, 16, v99
	v_and_b32_e32 v235, 0xffff0000, v99
	v_pk_fma_f32 v[146:147], v[62:63], v[238:239], v[134:135]
	v_pk_fma_f32 v[66:67], v[56:57], v[244:245], v[66:67]
	v_pk_fma_f32 v[148:149], v[44:45], v[248:249], v[148:149]
	v_pk_fma_f32 v[162:163], v[34:35], v[234:235], v[162:163]
	v_pk_fma_f32 v[146:147], v[58:59], v[246:247], v[146:147]
	v_pk_fma_f32 v[66:67], v[48:49], v[228:229], v[66:67]
	v_pk_fma_f32 v[148:149], v[40:41], v[232:233], v[148:149]
	v_lshlrev_b32_e32 v236, 16, v100
	v_and_b32_e32 v237, 0xffff0000, v100
	v_lshlrev_b32_e32 v240, 16, v102
	v_and_b32_e32 v241, 0xffff0000, v102
	v_cvt_pk_bf16_f32 v227, v162, v163
	v_pk_fma_f32 v[162:163], v[54:55], v[242:243], v[130:131]
	v_pk_fma_f32 v[146:147], v[50:51], v[230:231], v[146:147]
	v_pk_fma_f32 v[66:67], v[36:37], v[236:237], v[66:67]
	v_lshlrev_b32_e32 v238, 16, v101
	v_and_b32_e32 v239, 0xffff0000, v101
	v_pk_fma_f32 v[148:149], v[32:33], v[240:241], v[148:149]
	s_and_b64 s[18:19], s[18:19], s[20:21]
	ds_write_b128 v166, v[224:227] offset:1088
	v_pk_fma_f32 v[162:163], v[46:47], v[250:251], v[162:163]
	v_pk_fma_f32 v[146:147], v[38:39], v[238:239], v[146:147]
	v_cvt_pk_bf16_f32 v224, v66, v67
	v_pk_fma_f32 v[66:67], v[60:61], v[244:245], v[132:133]
	v_cvt_pk_bf16_f32 v225, v146, v147
	v_cvt_pk_bf16_f32 v226, v148, v149
	v_pk_fma_f32 v[148:149], v[52:53], v[248:249], v[128:129]
	v_pk_fma_f32 v[60:61], v[60:61], v[228:229], v[132:133]
	v_pk_fma_f32 v[52:53], v[52:53], v[232:233], v[128:129]
	s_waitcnt vmcnt(0)
	v_cndmask_b32_e64 v108, 0, v108, s[18:19]
	v_pk_fma_f32 v[162:163], v[42:43], v[234:235], v[162:163]
	v_lshlrev_b32_e32 v242, 16, v103
	v_and_b32_e32 v243, 0xffff0000, v103
	v_pk_fma_f32 v[146:147], v[62:63], v[246:247], v[134:135]
	v_pk_fma_f32 v[66:67], v[56:57], v[228:229], v[66:67]
	v_pk_fma_f32 v[148:149], v[44:45], v[232:233], v[148:149]
	v_lshlrev_b32_e32 v244, 16, v104
	v_and_b32_e32 v245, 0xffff0000, v104
	v_lshlrev_b32_e32 v248, 16, v106
	v_and_b32_e32 v249, 0xffff0000, v106
	v_pk_fma_f32 v[62:63], v[62:63], v[230:231], v[134:135]
	v_pk_fma_f32 v[56:57], v[56:57], v[236:237], v[60:61]
	v_pk_fma_f32 v[44:45], v[44:45], v[240:241], v[52:53]
	v_cndmask_b32_e64 v109, 0, v109, s[18:19]
	v_pk_fma_f32 v[162:163], v[34:35], v[242:243], v[162:163]
	v_pk_fma_f32 v[146:147], v[58:59], v[230:231], v[146:147]
	v_pk_fma_f32 v[66:67], v[48:49], v[236:237], v[66:67]
	v_pk_fma_f32 v[148:149], v[40:41], v[240:241], v[148:149]
	v_lshlrev_b32_e32 v246, 16, v105
	v_and_b32_e32 v247, 0xffff0000, v105
	v_pk_fma_f32 v[58:59], v[58:59], v[238:239], v[62:63]
	v_pk_fma_f32 v[48:49], v[48:49], v[244:245], v[56:57]
	v_pk_fma_f32 v[40:41], v[40:41], v[248:249], v[44:45]
	v_lshlrev_b32_e32 v44, 16, v108
	v_and_b32_e32 v45, 0xffff0000, v108
	v_cndmask_b32_e64 v110, 0, v110, s[18:19]
	v_cvt_pk_bf16_f32 v227, v162, v163
	v_pk_fma_f32 v[162:163], v[54:55], v[250:251], v[130:131]
	v_pk_fma_f32 v[146:147], v[50:51], v[238:239], v[146:147]
	v_pk_fma_f32 v[66:67], v[36:37], v[244:245], v[66:67]
	v_pk_fma_f32 v[54:55], v[54:55], v[234:235], v[130:131]
	v_pk_fma_f32 v[50:51], v[50:51], v[246:247], v[58:59]
	v_pk_fma_f32 v[36:37], v[36:37], v[44:45], v[48:49]
	v_lshlrev_b32_e32 v44, 16, v109
	v_and_b32_e32 v45, 0xffff0000, v109
	v_cndmask_b32_e64 v111, 0, v111, s[18:19]
	v_pk_fma_f32 v[162:163], v[46:47], v[234:235], v[162:163]
	v_pk_fma_f32 v[146:147], v[38:39], v[246:247], v[146:147]
	v_lshlrev_b32_e32 v250, 16, v107
	v_and_b32_e32 v251, 0xffff0000, v107
	v_pk_fma_f32 v[46:47], v[46:47], v[242:243], v[54:55]
	v_pk_fma_f32 v[38:39], v[38:39], v[44:45], v[50:51]
	v_lshlrev_b32_e32 v44, 16, v110
	v_and_b32_e32 v45, 0xffff0000, v110
	v_pk_fma_f32 v[162:163], v[42:43], v[242:243], v[162:163]
	v_pk_fma_f32 v[148:149], v[32:33], v[248:249], v[148:149]
	v_pk_fma_f32 v[42:43], v[42:43], v[250:251], v[46:47]
	v_pk_fma_f32 v[40:41], v[32:33], v[44:45], v[40:41]
	v_lshlrev_b32_e32 v32, 16, v111
	v_and_b32_e32 v33, 0xffff0000, v111
	ds_write_b128 v166, v[224:227] offset:1360
	v_pk_fma_f32 v[162:163], v[34:35], v[250:251], v[162:163]
	v_cvt_pk_bf16_f32 v224, v66, v67
	v_cvt_pk_bf16_f32 v225, v146, v147
	v_cvt_pk_bf16_f32 v226, v148, v149
	v_pk_fma_f32 v[42:43], v[34:35], v[32:33], v[42:43]
	v_cvt_pk_bf16_f32 v227, v162, v163
	ds_write_b128 v166, v[224:227] offset:1632
	v_cvt_pk_bf16_f32 v32, v36, v37
	v_cvt_pk_bf16_f32 v33, v38, v39
	v_cvt_pk_bf16_f32 v34, v40, v41
	v_cvt_pk_bf16_f32 v35, v42, v43
	s_cmp_eq_u32 s44, 0xff800000
	ds_write_b128 v166, v[32:35] offset:1904
	ds_write_b128 v168, v[112:115]
	ds_write_b128 v169, v[116:119]
	ds_write_b128 v170, v[120:123]
	ds_write_b128 v171, v[124:127]
	s_cbranch_scc1 .LBB0_308
; template <int dir>
; __device__ __forceinline__ void lru_pass(LAS unsigned char* lds, const Params& P, int b, int h, int q, bool dry) {
;     ...
;             LruTile nxt = cur;
;             if (sc < 8) { nxt = lru_tile(Z, ZC, b, h, dir, sc + 1); lru_load_rows(rows, nxt, tr, cgp);
; #pragma unroll
;                 for (int i = 0; i < NIN; ++i) { const int id = tid + i * NTHREADS;
;                     if (dir == 0) inr[i] = *(const u32x4*)(Zg + (size_t)(nxt.t0 + (id >> 2)) * 128 + (id & 3) * 8);
;                     else inr[i] = *(const u32x4*)(Hg + (size_t)(nxt.t0 + (id >> 3)) * DM + (id & 7) * 4); } }
	global_load_dwordx4 v[68:71], v[144:145], off offset:-1280
	global_load_dwordx4 v[72:75], v[144:145], off offset:-1024
	global_load_dwordx4 v[76:79], v[144:145], off offset:-768
	global_load_dwordx4 v[80:83], v[144:145], off offset:-512
	global_load_dwordx4 v[84:87], v[144:145], off offset:-256
	global_load_dwordx4 v[88:91], v[144:145], off
	global_load_dwordx4 v[92:95], v[144:145], off offset:256
	global_load_dwordx4 v[96:99], v[144:145], off offset:512
	global_load_dwordx4 v[100:103], v[144:145], off offset:768
	global_load_dwordx4 v[104:107], v[144:145], off offset:1024
	global_load_dwordx4 v[108:111], v[144:145], off offset:1280
	v_lshl_add_u64 v[32:33], v[142:143], 0, s[44:45]
	v_lshl_add_u64 v[34:35], v[252:253], 0, s[44:45]
	global_load_dwordx4 v[112:115], v[32:33], off sc1
	global_load_dwordx4 v[116:119], v[34:35], off sc1
	v_lshl_add_u64 v[32:33], v[154:155], 0, s[44:45]
	v_lshl_add_u64 v[34:35], v[150:151], 0, s[44:45]
	global_load_dwordx4 v[120:123], v[32:33], off sc1
	global_load_dwordx4 v[124:127], v[34:35], off sc1
	s_movk_i32 s28, 0x800
	s_mov_b32 s20, s25
	s_branch .LBB0_309

; #define LDS_BARRIER() do { asm volatile("s_waitcnt lgkmcnt(0)" ::: "memory"); __builtin_amdgcn_s_barrier(); asm volatile("" ::: "memory"); } while (0)
;     __device__ __forceinline__ void fused(f32x4 (&acc)[2][2][4][2], const Unit& u, int wr, int wc, int fr, int fq, LAS unsigned char* lds, int wid, int lane) const {
;     ...
;         if (wid == 0) { unsigned sp = 0;
;             while ((unsigned)__builtin_amdgcn_readfirstlane(__hip_atomic_load(cnt + 64 * u.pm, __ATOMIC_RELAXED, __HIP_MEMORY_SCOPE_AGENT)) < 16u) { __builtin_amdgcn_s_sleep(1); if (++sp > (1u << 20)) break; }
;             __builtin_amdgcn_fence(__ATOMIC_ACQUIRE, "agent");
;             asm volatile("s_waitcnt vmcnt(0)" ::: "memory"); }
;         LDS_BARRIER();
;         if (tid < 256) { const float* sp = xs + ((size_t)u.pm * 256 + tid) * 4; float t = 0.f;
; #pragma unroll
;             for (int k = 0; k < 4; ++k) t += __hip_atomic_load(sp + k, __ATOMIC_RELAXED, __HIP_MEMORY_SCOPE_AGENT);
;             S[tid] = 1.0f / sqrtf(t * (1.0f / DM) + 1e-6f); }
.LBB0_459:
	global_load_dword v3, v2, s[4:5] sc1
	s_mov_b64 s[16:17], -1
	s_waitcnt vmcnt(0)
	v_readfirstlane_b32 s6, v3
	s_cmp_gt_u32 s6, 15
	s_cbranch_scc1 .LBB0_458
	s_add_i32 s3, s3, -1
	s_cmp_eq_u32 s3, 0
	s_cselect_b64 s[16:17], -1, 0
	s_sleep 1
	s_branch .LBB0_458
.LBB0_461:
	s_waitcnt vmcnt(0)
.LBB0_462:
	s_waitcnt lgkmcnt(0)
	s_barrier
	s_and_saveexec_b64 s[4:5], s[0:1]
	s_cbranch_execz .LBB0_464
	s_ashr_i32 s15, s14, 31
	s_lshl_b64 s[0:1], s[14:15], 12
	s_add_u32 s0, s12, s0
	s_addc_u32 s1, s13, s1
	v_lshl_add_u64 v[2:3], v[0:1], 4, s[0:1]
	global_load_dword v1, v[2:3], off sc1
	global_load_dword v4, v[2:3], off offset:4 sc1
	global_load_dword v5, v[2:3], off offset:8 sc1
	s_nop 0
	global_load_dword v2, v[2:3], off offset:12 sc1
	v_mov_b32_e32 v3, 0x358637bd
	s_mov_b32 s0, 0xf800000
	v_lshl_add_u32 v0, v0, 2, 0
	s_waitcnt vmcnt(3)
	v_add_f32_e32 v1, 0, v1
	s_waitcnt vmcnt(2)
	v_add_f32_e32 v1, v1, v4
	s_waitcnt vmcnt(1)
	v_add_f32_e32 v1, v1, v5
	s_waitcnt vmcnt(0)
	v_add_f32_e32 v1, v1, v2
	v_fmac_f32_e32 v3, 0x3a800000, v1
	v_mul_f32_e32 v1, 0x4f800000, v3
	v_cmp_gt_f32_e32 vcc, s0, v3
	s_nop 1
	v_cndmask_b32_e32 v1, v3, v1, vcc
	v_sqrt_f32_e32 v2, v1
	v_mov_b32_e32 v3, 0x260
	v_add_u32_e32 v4, -1, v2
	v_add_u32_e32 v5, 1, v2
	v_fma_f32 v6, -v4, v2, v1
	v_fma_f32 v7, -v5, v2, v1
	v_cmp_ge_f32_e64 s[0:1], 0, v6
	s_nop 1
	v_cndmask_b32_e64 v2, v2, v4, s[0:1]
	v_cmp_lt_f32_e64 s[0:1], 0, v7
	s_nop 1
	v_cndmask_b32_e64 v2, v2, v5, s[0:1]
	v_mul_f32_e32 v4, 0x37800000, v2
	v_cndmask_b32_e32 v2, v2, v4, vcc
	v_cmp_class_f32_e32 vcc, v1, v3
	s_nop 1
	v_cndmask_b32_e32 v1, v2, v1, vcc
	v_div_scale_f32 v2, s[0:1], v1, v1, 1.0
	v_rcp_f32_e32 v3, v2
	v_div_scale_f32 v4, vcc, 1.0, v1, 1.0
	v_fma_f32 v5, -v2, v3, 1.0
	v_fmac_f32_e32 v3, v5, v3
	v_mul_f32_e32 v5, v4, v3
	v_fma_f32 v6, -v2, v5, v4
	v_fmac_f32_e32 v5, v6, v3
	v_fma_f32 v2, -v2, v5, v4
	v_div_fmas_f32 v2, v2, v3, v5
	v_div_fixup_f32 v1, v2, v1, 1.0
	ds_write_b32 v0, v1 offset:4096
